# GLA scan section D: output-tile parking (DPP exchange, bf16 pack, LDS stores) spread through the state-update MFMA shadows; state-update temporaries renamed to idle registers; park address hoisted
# speedup vs baseline: 1.0057x; 1.0057x over previous
; __device__ __forceinline__ int crow(int r, int hi) { return (r & 3) + 8 * (r >> 2) + 4 * hi; }
; __device__ __forceinline__ unsigned pk2(float lo, float hi) { f32x2_t v = {lo, hi}; bf16x2_t b = __builtin_convertvector(v, bf16x2_t); return __builtin_bit_cast(unsigned, b); }
; __device__ __forceinline__ u16 f2bf(float f) { return (u16)(pk2(f, 0.f) & 0xffffu); }
; __device__ __forceinline__ void scan_unit(const int unit, const Args& a, unsigned char* lds, const int mk_wid) {
;     ...
;     { const int l_ = MK_TID & 63, r32 = l_ & 31, hi = l_ >> 5; const float* up = a.in[dir ? 12 : 10] + (size_t)(8 * hi) * 512 + h * 128 + (wid & 3) * 32 + r32;
;       v4u w; w.x = pk2(up[0], up[512]); w.y = pk2(up[2 * 512], up[3 * 512]); w.z = pk2(up[4 * 512], up[5 * 512]); w.w = pk2(up[6 * 512], up[7 * 512]);
;       upf = __builtin_bit_cast(bf16x8, w); biasc = a.in[dir ? 13 : 11][h * 128 + (wid & 3) * 32 + r32]; }
;     u16* qe = (u16*)(lds + L_QE); u16* ke = (u16*)(lds + L_KE); u16* am = (u16*)(lds + L_AM);
;     float* las = (float*)(lds + L_LAS); float* gs = (float*)(lds + L_GS); float* dl = (float*)(lds + L_DL);
;     const int ldsb = (int)(uintptr_t)lds;
;     u16* ot = (u16*)(lds + L_LAS);
;     int pend_cc = -1;
;     ...
;     f32x16 S[4]; S[0] = f32x16{}; S[1] = f32x16{}; S[2] = f32x16{}; S[3] = f32x16{};
;     bf16x8 qraw[2], kraw[2], vraw[4]; bf16x8 lraw = bf16x8{};
;     ...
;     GLA_LOAD(0);
;     ...
;               { u16* ow = ot + (4 * hi) * 256 + vt * 32 + r32;
; #pragma unroll
;                 for (int r = 0; r < 16; ++r) { const int i0 = crow(r, 0); ow[i0 * 256] = f2bf(o0[r]); ow[(i0 + 32) * 256] = f2bf(o1[r]); } }
.Lscan_qk_done2:
	v_mov_b32_e32 v128, 0
	v_mov_b32_e32 v129, 0
	v_mov_b32_e32 v130, 0
	v_mov_b32_e32 v131, 0
	v_mov_b32_e32 v132, 0
	v_mov_b32_e32 v133, 0
	v_mov_b32_e32 v134, 0
	v_mov_b32_e32 v135, 0
	v_mbcnt_lo_u32_b32 v66, -1, 0
	v_mbcnt_hi_u32_b32 v66, -1, v66
	v_bfe_u32 v67, v66, 4, 1
	v_lshlrev_b32_e32 v67, 3, v67
	v_bfe_u32 v68, v66, 2, 2
	v_add_u32_e32 v67, v67, v68
	s_and_b32 s96, s70, 3
	s_lshl_b32 s96, s96, 4
	v_add_u32_e32 v67, s96, v67
	v_lshrrev_b32_e32 v68, 5, v66
	v_lshlrev_b32_e32 v68, 6, v68
	v_and_b32_e32 v69, 3, v66
	v_lshl_add_u32 v68, v69, 4, v68
	s_lshr_b32 s96, s70, 2
	s_lshl_b32 s96, s96, 8
	v_add_u32_e32 v68, s96, v68
	v_sub_u32_e32 v69, 63, v67
	v_cndmask_b32_e64 v69, v69, v67, s[2:3]
	v_add_u32_e32 v69, s12, v69
	v_lshl_add_u32 v247, v69, 11, v68
	v_add_u32_e32 v248, 0x80, v247
	v_add_u32_e32 v67, 4, v67
	v_sub_u32_e32 v69, 63, v67
	v_cndmask_b32_e64 v69, v69, v67, s[2:3]
	v_add_u32_e32 v69, s12, v69
	v_lshl_add_u32 v249, v69, 11, v68
	v_add_u32_e32 v250, 0x80, v249
	v_mbcnt_lo_u32_b32 v66, -1, 0
	v_mbcnt_hi_u32_b32 v66, -1, v66
	s_lshr_b32 s96, s70, 2
	s_lshl_b32 s96, s96, 5
	v_and_b32_e32 v67, 31, v66
	v_add_u32_e32 v67, s96, v67
	v_sub_u32_e32 v68, 63, v67
	v_cndmask_b32_e64 v67, v68, v67, s[2:3]
	v_add_u32_e32 v67, s12, v67
	v_bfe_u32 v68, v66, 5, 1
	v_lshlrev_b32_e32 v68, 4, v68
	v_lshl_add_u32 v251, v67, 6, v68
	s_bitcmp1_b32 s8, 0
	s_cselect_b32 s97, 3, 0
	s_lshl_b32 s97, s97, 12
	v_add_u32_e32 v70, s97, v251
	v_mov_b32_e32 v71, 0
	v_lshl_add_u64 v[70:71], v[152:153], 0, v[70:71]
	global_load_dwordx4 v[96:99], v[70:71], off
	v_lshrrev_b32_e32 v67, 3, v66
	v_add_u32_e32 v67, s96, v67
	v_and_b32_e32 v68, 7, v66
	v_lshlrev_b32_e32 v68, 4, v68
	s_and_b32 s97, s70, 3
	s_lshl_b32 s97, s97, 7
	v_add_u32_e32 v68, s97, v68
	v_lshl_add_u32 v253, v67, 9, v68
	v_add_u32_e32 v253, s9, v253
	v_sub_u32_e32 v69, 63, v67
	v_cndmask_b32_e64 v67, v69, v67, s[2:3]
	v_lshl_add_u32 v252, v67, 11, v68
	v_mbcnt_lo_u32_b32 v64, -1, 0
	v_mbcnt_hi_u32_b32 v64, -1, v64
	s_cmp_gt_u32 s70, 0
	s_cselect_b32 s97, 1.0, 0
	v_mov_b32_e32 v238, s97
	s_cmp_gt_u32 s70, 1
	s_cselect_b32 s97, 1.0, 0
	v_mov_b32_e32 v239, s97
	s_cmp_gt_u32 s70, 2
	s_cselect_b32 s97, 1.0, 0
	v_mov_b32_e32 v240, s97
	s_cmp_gt_u32 s70, 3
	s_cselect_b32 s97, 1.0, 0
	v_mov_b32_e32 v241, s97
	s_cmp_gt_u32 s70, 4
	s_cselect_b32 s97, 1.0, 0
	v_mov_b32_e32 v242, s97
	s_cmp_gt_u32 s70, 5
	s_cselect_b32 s97, 1.0, 0
	v_mov_b32_e32 v243, s97
	s_cmp_gt_u32 s70, 6
	s_cselect_b32 s97, 1.0, 0
	v_mov_b32_e32 v244, s97
	s_mul_i32 s99, s70, 0x880
	v_and_b32_e32 v66, 2, v64
	v_lshlrev_b32_e32 v66, 1, v66
	v_and_b32_e32 v67, 4, v64
	v_lshrrev_b32_e32 v67, 1, v67
	v_and_b32_e32 v70, 0xfffffff9, v64
	v_or3_b32 v66, v66, v67, v70
	v_lshl_add_u32 v254, v66, 2, s99
	s_lshr_b32 s98, s70, 1
	s_lshl_b32 s98, s98, 12
	s_and_b32 s99, s70, 1
	s_lshl_b32 s99, s99, 8
	s_add_i32 s98, s98, s99
	v_lshrrev_b32_e32 v66, 4, v64
	v_lshlrev_b32_e32 v66, 9, v66
	v_and_b32_e32 v70, 15, v64
	v_lshl_add_u32 v66, v70, 2, v66
	v_add_u32_e32 v255, s98, v66
	s_lshr_b32 s98, s70, 2
	s_lshl_b32 s98, s98, 12
	s_and_b32 s99, s70, 3
	s_lshl_b32 s99, s99, 7
	s_add_i32 s98, s98, s99
	s_add_i32 s98, s98, 0x20000
	v_lshrrev_b32_e32 v66, 5, v64
	v_lshlrev_b32_e32 v66, 9, v66
	v_and_b32_e32 v70, 31, v64
	v_lshl_add_u32 v66, v70, 2, v66
	v_add_u32_e32 v169, s98, v66
	v_mbcnt_lo_u32_b32 v64, -1, 0
	v_mbcnt_hi_u32_b32 v64, -1, v64
	v_lshrrev_b32_e32 v66, 5, v64
	v_lshlrev_b32_e32 v66, 11, v66
	v_and_b32_e32 v67, 31, v64
	v_lshlrev_b32_e32 v70, 1, v67
	v_add3_u32 v66, s49, v66, v70
	v_and_b32_e32 v67, 1, v67
	v_mul_u32_u24_e32 v67, 0x1fe, v67
	v_add_u32_e32 v246, v66, v67

; __device__ __forceinline__ unsigned pk2(float lo, float hi) { f32x2_t v = {lo, hi}; bf16x2_t b = __builtin_convertvector(v, bf16x2_t); return __builtin_bit_cast(unsigned, b); }
; #define GLA_SBAR() __builtin_amdgcn_sched_barrier(0)
; __device__ __forceinline__ void scan_unit(const int unit, const Args& a, unsigned char* lds, const int mk_wid) {
;     ...
;               f32x16 o0 = f32x16{}, o1 = f32x16{};
; #pragma unroll
;               for (int ct = 0; ct < 4; ++ct)
; #pragma unroll
;                 for (int kb = 0; kb < 2; ++kb) { const int cb = ct * 32 + kb * 16;
;                     v4u sw; sw.x = pk2(S[ct][8 * kb + 0], S[ct][8 * kb + 1]); sw.y = pk2(S[ct][8 * kb + 2], S[ct][8 * kb + 3]); sw.z = pk2(S[ct][8 * kb + 4], S[ct][8 * kb + 5]); sw.w = pk2(S[ct][8 * kb + 6], S[ct][8 * kb + 7]);
;                     const bf16x8 sb = __builtin_bit_cast(bf16x8, sw);
;                     { const u16* p0 = qe + r32 * QP + cb + 4 * hi; const v2u lo = *(const v2u*)p0, hh = *(const v2u*)(p0 + 8); v4u aw = {lo.x, lo.y, hh.x, hh.y};
;                       o0 = __builtin_amdgcn_mfma_f32_32x32x16_bf16(__builtin_bit_cast(bf16x8, aw), sb, o0, 0, 0, 0); }
;                     { const u16* p1 = qe + (32 + r32) * QP + cb + 4 * hi; const v2u lo = *(const v2u*)p1, hh = *(const v2u*)(p1 + 8); v4u aw = {lo.x, lo.y, hh.x, hh.y};
;                       o1 = __builtin_amdgcn_mfma_f32_32x32x16_bf16(__builtin_bit_cast(bf16x8, aw), sb, o1, 0, 0, 0); } }
;               GLA_LOADV();
;               asm volatile("s_waitcnt lgkmcnt(0)" ::: "memory"); GLA_SBAR();
;               { const u16* a0 = am + r32 * AP + hi * 8; const u16* a1 = am + (32 + r32) * AP + hi * 8;
;                 o0 = __builtin_amdgcn_mfma_f32_32x32x16_bf16(*(const bf16x8*)(a0), GLA_PK(vl0, vh0), o0, 0, 0, 0);
;                 o0 = __builtin_amdgcn_mfma_f32_32x32x16_bf16(*(const bf16x8*)(a0 + 16), GLA_PK(vl1, vh1), o0, 0, 0, 0);
;                 o1 = __builtin_amdgcn_mfma_f32_32x32x16_bf16(*(const bf16x8*)(a1), GLA_PK(vl0, vh0), o1, 0, 0, 0);
;                 o1 = __builtin_amdgcn_mfma_f32_32x32x16_bf16(*(const bf16x8*)(a1 + 16), GLA_PK(vl1, vh1), o1, 0, 0, 0);
;                 o1 = __builtin_amdgcn_mfma_f32_32x32x16_bf16(*(const bf16x8*)(a1 + 32), GLA_PK(vl2, vh2), o1, 0, 0, 0);
;                 o1 = __builtin_amdgcn_mfma_f32_32x32x16_bf16(*(const bf16x8*)(a1 + 48), GLA_PK(vl3, vh3), o1, 0, 0, 0); }
.LBB0_442:
	v_and_b32_e32 v168, 31, v64
	v_mul_u32_u24_e32 v64, 0x110, v168
	v_lshlrev_b32_e32 v65, 4, v157
	v_add3_u32 v144, 0, v64, v65
	ds_read_b128 v[170:173], v144
	ds_read_b128 v[174:177], v144 offset:32
	ds_read_b128 v[178:181], v144 offset:8704
	ds_read_b128 v[182:185], v144 offset:8736
	ds_read_b128 v[186:189], v144 offset:64
	ds_read_b128 v[190:193], v144 offset:8768
	ds_read_b128 v[194:197], v144 offset:96
	ds_read_b128 v[198:201], v144 offset:8800
	ds_read_b128 v[202:205], v144 offset:128
	ds_read_b128 v[206:209], v144 offset:8832
	ds_read_b128 v[210:213], v144 offset:160
	ds_read_b128 v[214:217], v144 offset:8864
	ds_read_b128 v[218:221], v144 offset:192
	ds_read_b128 v[222:225], v144 offset:8896
	ds_read_b128 v[226:229], v144 offset:224
	v_cvt_pk_bf16_f32 v80, v0, v1
	v_cvt_pk_bf16_f32 v81, v2, v3
	v_cvt_pk_bf16_f32 v82, v4, v5
	v_cvt_pk_bf16_f32 v83, v6, v7
	s_waitcnt lgkmcnt(14)
	s_nop 0
	v_mfma_f32_32x32x16_bf16 v[64:79], v[170:173], v[80:83], 0
	ds_read_b128 v[230:233], v144 offset:8928
	v_cvt_pk_bf16_f32 v140, v8, v9
	v_cvt_pk_bf16_f32 v141, v10, v11
	v_cvt_pk_bf16_f32 v142, v12, v13
	v_cvt_pk_bf16_f32 v143, v14, v15
	v_cvt_pk_bf16_f32 v160, v56, v57
	v_cvt_pk_bf16_f32 v161, v58, v59
	v_cvt_pk_bf16_f32 v162, v60, v61
	v_cvt_pk_bf16_f32 v163, v62, v63
	s_waitcnt lgkmcnt(14)
	s_nop 0
	v_mfma_f32_32x32x16_bf16 v[64:79], v[174:177], v[140:143], v[64:79]
	s_waitcnt lgkmcnt(13)
	v_mfma_f32_32x32x16_bf16 v[80:95], v[178:181], v[80:83], 0
	s_waitcnt lgkmcnt(12)
	v_mfma_f32_32x32x16_bf16 v[80:95], v[182:185], v[140:143], v[80:95]
	v_cvt_pk_bf16_f32 v140, v16, v17
	v_cvt_pk_bf16_f32 v141, v18, v19
	v_cvt_pk_bf16_f32 v142, v20, v21
	v_cvt_pk_bf16_f32 v143, v22, v23
	s_waitcnt lgkmcnt(11)
	s_nop 0
	v_mfma_f32_32x32x16_bf16 v[64:79], v[186:189], v[140:143], v[64:79]
	s_waitcnt lgkmcnt(10)
	v_mfma_f32_32x32x16_bf16 v[80:95], v[190:193], v[140:143], v[80:95]
	v_cvt_pk_bf16_f32 v140, v24, v25
	v_cvt_pk_bf16_f32 v141, v26, v27
	v_cvt_pk_bf16_f32 v142, v28, v29
	v_cvt_pk_bf16_f32 v143, v30, v31
	s_waitcnt lgkmcnt(9)
	s_nop 0
	v_mfma_f32_32x32x16_bf16 v[64:79], v[194:197], v[140:143], v[64:79]
	s_waitcnt lgkmcnt(8)
	v_mfma_f32_32x32x16_bf16 v[80:95], v[198:201], v[140:143], v[80:95]
	v_cvt_pk_bf16_f32 v140, v32, v33
	v_cvt_pk_bf16_f32 v141, v34, v35
	v_cvt_pk_bf16_f32 v142, v36, v37
	v_cvt_pk_bf16_f32 v143, v38, v39
	s_waitcnt lgkmcnt(7)
	s_nop 0
	v_mfma_f32_32x32x16_bf16 v[64:79], v[202:205], v[140:143], v[64:79]
	s_waitcnt lgkmcnt(6)
	v_mfma_f32_32x32x16_bf16 v[80:95], v[206:209], v[140:143], v[80:95]
	v_cvt_pk_bf16_f32 v140, v40, v41
	v_cvt_pk_bf16_f32 v141, v42, v43
	v_cvt_pk_bf16_f32 v142, v44, v45
	v_cvt_pk_bf16_f32 v143, v46, v47
	s_waitcnt lgkmcnt(5)
	s_nop 0
	v_mfma_f32_32x32x16_bf16 v[64:79], v[210:213], v[140:143], v[64:79]
	s_waitcnt lgkmcnt(4)
	v_mfma_f32_32x32x16_bf16 v[80:95], v[214:217], v[140:143], v[80:95]
	v_cvt_pk_bf16_f32 v140, v48, v49
	v_cvt_pk_bf16_f32 v141, v50, v51
	v_cvt_pk_bf16_f32 v142, v52, v53
	v_cvt_pk_bf16_f32 v143, v54, v55
	s_waitcnt lgkmcnt(3)
	s_nop 0
	v_mfma_f32_32x32x16_bf16 v[64:79], v[218:221], v[140:143], v[64:79]
	s_waitcnt lgkmcnt(2)
	v_mfma_f32_32x32x16_bf16 v[80:95], v[222:225], v[140:143], v[80:95]
	v_mul_u32_u24_e32 v236, 0x90, v168
	v_lshlrev_b32_e32 v237, 4, v157
	v_add3_u32 v236, s57, v236, v237
	ds_read_b128 v[170:173], v236
	ds_read_b128 v[174:177], v236 offset:32
	ds_read_b128 v[178:181], v236 offset:4608
	ds_read_b128 v[182:185], v236 offset:4640
	ds_read_b128 v[186:189], v236 offset:4672
	ds_read_b128 v[190:193], v236 offset:4704
	ds_read_b64_tr_b16 v[136:137], v158 offset:0
	s_waitcnt lgkmcnt(8)
	v_mfma_f32_32x32x16_bf16 v[64:79], v[226:229], v[160:163], v[64:79]
	ds_read_b64_tr_b16 v[138:139], v158 offset:0x800
	ds_read_b64_tr_b16 v[140:141], v158 offset:0x1000
	ds_read_b64_tr_b16 v[142:143], v158 offset:0x1800
	ds_read_b64_tr_b16 v[144:145], v158 offset:0x2000
	ds_read_b64_tr_b16 v[146:147], v158 offset:0x2800
	ds_read_b64_tr_b16 v[148:149], v158 offset:0x3000
	ds_read_b64_tr_b16 v[150:151], v158 offset:0x3800
	s_waitcnt lgkmcnt(0)
	v_mfma_f32_32x32x16_bf16 v[80:95], v[230:233], v[160:163], v[80:95]
	s_mov_b32 s34, s42
	v_mfma_f32_32x32x16_bf16 v[64:79], v[170:173], v[136:139], v[64:79]
	v_mfma_f32_32x32x16_bf16 v[64:79], v[174:177], v[140:143], v[64:79]
	v_mfma_f32_32x32x16_bf16 v[80:95], v[178:181], v[136:139], v[80:95]
	v_mfma_f32_32x32x16_bf16 v[80:95], v[182:185], v[140:143], v[80:95]
	v_mfma_f32_32x32x16_bf16 v[80:95], v[186:189], v[144:147], v[80:95]
	v_mfma_f32_32x32x16_bf16 v[80:95], v[190:193], v[148:151], v[80:95]
; __device__ __forceinline__ int crow(int r, int hi) { return (r & 3) + 8 * (r >> 2) + 4 * hi; }
; __device__ __forceinline__ int v_rd_base(int lane) { return ((lane & 3) << 3) | (((lane >> 2) & 3) << 6) | (((lane >> 4) & 1) << 5) | (((lane >> 5) & 1) << 8); }
; __device__ __forceinline__ u16 f2bf(float f) { return (u16)(pk2(f, 0.f) & 0xffffu); }
; #define GLA_SBAR() __builtin_amdgcn_sched_barrier(0)
; __device__ __forceinline__ void scan_unit(const int unit, const Args& a, unsigned char* lds, const int mk_wid) {
;     ...
;               { u16* ow = ot + (4 * hi) * 256 + vt * 32 + r32;
; #pragma unroll
;                 for (int r = 0; r < 16; ++r) { const int i0 = crow(r, 0); ow[i0 * 256] = f2bf(o0[r]); ow[(i0 + 32) * 256] = f2bf(o1[r]); } }
;     ...
; #pragma unroll
;           for (int ct = 0; ct < 4; ++ct) { const int kb_ = ldsb + L_KD + v_rd_base(lane) + ct * 512;
;               const s16x4 al0 = tr_read<v_rd_off(0, 0, 0)>(kb_), ah0 = tr_read<v_rd_off(0, 0, 1)>(kb_), al1 = tr_read<v_rd_off(0, 1, 0)>(kb_), ah1 = tr_read<v_rd_off(0, 1, 1)>(kb_);
;               const s16x4 al2 = tr_read<v_rd_off(0, 2, 0)>(kb_), ah2 = tr_read<v_rd_off(0, 2, 1)>(kb_), al3 = tr_read<v_rd_off(0, 3, 0)>(kb_), ah3 = tr_read<v_rd_off(0, 3, 1)>(kb_);
;               const float* dp = dl + ct * 32 + 4 * hi;
; #pragma unroll
;               for (int rg = 0; rg < 4; ++rg) { const f32x4 d4 = *(const f32x4*)(dp + 8 * rg);
;                   S[ct][4 * rg + 0] *= d4.x; S[ct][4 * rg + 1] *= d4.y; S[ct][4 * rg + 2] *= d4.z; S[ct][4 * rg + 3] *= d4.w; }
;               asm volatile("s_waitcnt lgkmcnt(0)" ::: "memory"); GLA_SBAR();
;               S[ct] = __builtin_amdgcn_mfma_f32_32x32x16_bf16(GLA_PK(al0, ah0), GLA_PK(vl0, vh0), S[ct], 0, 0, 0);
;               S[ct] = __builtin_amdgcn_mfma_f32_32x32x16_bf16(GLA_PK(al1, ah1), GLA_PK(vl1, vh1), S[ct], 0, 0, 0);
;               S[ct] = __builtin_amdgcn_mfma_f32_32x32x16_bf16(GLA_PK(al2, ah2), GLA_PK(vl2, vh2), S[ct], 0, 0, 0);
;               S[ct] = __builtin_amdgcn_mfma_f32_32x32x16_bf16(GLA_PK(al3, ah3), GLA_PK(vl3, vh3), S[ct], 0, 0, 0); } }
.LBB0_443:
	s_cmp_lg_u32 0, -1
	s_cselect_b32 s4, 0, 0
	s_add_i32 s5, s4, 0x8800
	v_lshl_add_u32 v202, v157, 4, 0
	v_add_u32_e32 v218, s5, v154
	v_add_u32_e32 v157, 0x1fc00, v202
	ds_read_b64_tr_b16 v[202:203], v218 offset:0
	ds_read_b64_tr_b16 v[204:205], v218 offset:0x800
	ds_read_b64_tr_b16 v[206:207], v218 offset:0x1000
	ds_read_b64_tr_b16 v[208:209], v218 offset:0x1800
	ds_read_b64_tr_b16 v[210:211], v218 offset:0x2000
	ds_read_b64_tr_b16 v[212:213], v218 offset:0x2800
	ds_read_b64_tr_b16 v[214:215], v218 offset:0x3000
	ds_read_b64_tr_b16 v[216:217], v218 offset:0x3800
	ds_read_b128 v[218:221], v157
	ds_read_b128 v[222:225], v157 offset:32
	ds_read_b128 v[226:229], v157 offset:64
	s_mov_b32 vcc_lo, 0x55555555
	s_mov_b32 vcc_hi, 0x55555555
	s_nop 1
	v_cndmask_b32_dpp v170, v65, v64, vcc quad_perm:[1,0,3,2] row_mask:0xf bank_mask:0xf
	v_cndmask_b32_dpp v171, v67, v66, vcc quad_perm:[1,0,3,2] row_mask:0xf bank_mask:0xf
	v_cndmask_b32_dpp v172, v69, v68, vcc quad_perm:[1,0,3,2] row_mask:0xf bank_mask:0xf
	v_cndmask_b32_dpp v173, v71, v70, vcc quad_perm:[1,0,3,2] row_mask:0xf bank_mask:0xf
	v_cndmask_b32_dpp v174, v73, v72, vcc quad_perm:[1,0,3,2] row_mask:0xf bank_mask:0xf
	v_cndmask_b32_dpp v175, v75, v74, vcc quad_perm:[1,0,3,2] row_mask:0xf bank_mask:0xf
	v_cndmask_b32_dpp v176, v77, v76, vcc quad_perm:[1,0,3,2] row_mask:0xf bank_mask:0xf
	v_cndmask_b32_dpp v177, v79, v78, vcc quad_perm:[1,0,3,2] row_mask:0xf bank_mask:0xf
	s_waitcnt lgkmcnt(2)
	v_pk_mul_f32 v[0:1], v[0:1], v[218:219]
	v_pk_mul_f32 v[2:3], v[2:3], v[220:221]
	ds_read_b128 v[218:221], v157 offset:96
	s_waitcnt lgkmcnt(0)
	s_waitcnt lgkmcnt(2)
	v_pk_mul_f32 v[4:5], v[4:5], v[222:223]
	v_pk_mul_f32 v[6:7], v[6:7], v[224:225]
	s_waitcnt lgkmcnt(1)
	v_pk_mul_f32 v[8:9], v[8:9], v[226:227]
	v_pk_mul_f32 v[10:11], v[10:11], v[228:229]
	s_waitcnt lgkmcnt(0)
	v_pk_mul_f32 v[12:13], v[12:13], v[218:219]
	v_pk_mul_f32 v[14:15], v[14:15], v[220:221]
	s_nop 1
	v_mfma_f32_32x32x16_bf16 v[0:15], v[202:205], v[136:139], v[0:15]
	v_cndmask_b32_dpp v178, v81, v80, vcc quad_perm:[1,0,3,2] row_mask:0xf bank_mask:0xf
	v_cndmask_b32_dpp v179, v83, v82, vcc quad_perm:[1,0,3,2] row_mask:0xf bank_mask:0xf
	v_cndmask_b32_dpp v180, v85, v84, vcc quad_perm:[1,0,3,2] row_mask:0xf bank_mask:0xf
	v_cndmask_b32_dpp v181, v87, v86, vcc quad_perm:[1,0,3,2] row_mask:0xf bank_mask:0xf
	v_cndmask_b32_dpp v182, v89, v88, vcc quad_perm:[1,0,3,2] row_mask:0xf bank_mask:0xf
	v_cndmask_b32_dpp v183, v91, v90, vcc quad_perm:[1,0,3,2] row_mask:0xf bank_mask:0xf
	v_cndmask_b32_dpp v184, v93, v92, vcc quad_perm:[1,0,3,2] row_mask:0xf bank_mask:0xf
	v_cndmask_b32_dpp v185, v95, v94, vcc quad_perm:[1,0,3,2] row_mask:0xf bank_mask:0xf
	s_add_i32 s5, s4, 0x8a00
	v_add_u32_e32 v226, s5, v154
	ds_read_b64_tr_b16 v[202:203], v226 offset:0
	ds_read_b64_tr_b16 v[204:205], v226 offset:0x800
	ds_read_b64_tr_b16 v[218:219], v226 offset:0x1000
	ds_read_b64_tr_b16 v[220:221], v226 offset:0x1800
	ds_read_b64_tr_b16 v[222:223], v226 offset:0x2000
	v_mfma_f32_32x32x16_bf16 v[0:15], v[206:209], v[140:143], v[0:15]
	s_mov_b32 vcc_lo, 0xaaaaaaaa
	s_mov_b32 vcc_hi, 0xaaaaaaaa
	s_nop 1
	v_cndmask_b32_dpp v186, v64, v65, vcc quad_perm:[1,0,3,2] row_mask:0xf bank_mask:0xf
	v_cndmask_b32_dpp v187, v66, v67, vcc quad_perm:[1,0,3,2] row_mask:0xf bank_mask:0xf
	v_cndmask_b32_dpp v188, v68, v69, vcc quad_perm:[1,0,3,2] row_mask:0xf bank_mask:0xf
	v_cndmask_b32_dpp v189, v70, v71, vcc quad_perm:[1,0,3,2] row_mask:0xf bank_mask:0xf
	v_cndmask_b32_dpp v190, v72, v73, vcc quad_perm:[1,0,3,2] row_mask:0xf bank_mask:0xf
	v_cndmask_b32_dpp v191, v74, v75, vcc quad_perm:[1,0,3,2] row_mask:0xf bank_mask:0xf
	v_cndmask_b32_dpp v192, v76, v77, vcc quad_perm:[1,0,3,2] row_mask:0xf bank_mask:0xf
	v_cndmask_b32_dpp v193, v78, v79, vcc quad_perm:[1,0,3,2] row_mask:0xf bank_mask:0xf
	ds_read_b64_tr_b16 v[224:225], v226 offset:0x2800
	ds_read_b64_tr_b16 v[206:207], v226 offset:0x3000
	ds_read_b64_tr_b16 v[208:209], v226 offset:0x3800
	ds_read_b128 v[226:229], v157 offset:128
	ds_read_b128 v[230:233], v157 offset:160
	s_waitcnt lgkmcnt(1)
	v_mul_f32_e64 v16, v16, v226
	v_mul_f32_e64 v17, v17, v227
	v_mfma_f32_32x32x16_bf16 v[0:15], v[210:213], v[144:147], v[0:15]
	v_cndmask_b32_dpp v194, v80, v81, vcc quad_perm:[1,0,3,2] row_mask:0xf bank_mask:0xf
	v_cndmask_b32_dpp v195, v82, v83, vcc quad_perm:[1,0,3,2] row_mask:0xf bank_mask:0xf
	v_cndmask_b32_dpp v196, v84, v85, vcc quad_perm:[1,0,3,2] row_mask:0xf bank_mask:0xf
	v_cndmask_b32_dpp v197, v86, v87, vcc quad_perm:[1,0,3,2] row_mask:0xf bank_mask:0xf
	v_cndmask_b32_dpp v198, v88, v89, vcc quad_perm:[1,0,3,2] row_mask:0xf bank_mask:0xf
	v_cndmask_b32_dpp v199, v90, v91, vcc quad_perm:[1,0,3,2] row_mask:0xf bank_mask:0xf
	v_cndmask_b32_dpp v200, v92, v93, vcc quad_perm:[1,0,3,2] row_mask:0xf bank_mask:0xf
	v_cndmask_b32_dpp v201, v94, v95, vcc quad_perm:[1,0,3,2] row_mask:0xf bank_mask:0xf
	v_mul_f32_e64 v18, v18, v228
	v_mul_f32_e64 v19, v19, v229
	ds_read_b128 v[226:229], v157 offset:192
	ds_read_b128 v[210:213], v157 offset:224
	s_waitcnt lgkmcnt(0)
; __device__ __forceinline__ int crow(int r, int hi) { return (r & 3) + 8 * (r >> 2) + 4 * hi; }
; __device__ __forceinline__ int v_rd_base(int lane) { return ((lane & 3) << 3) | (((lane >> 2) & 3) << 6) | (((lane >> 4) & 1) << 5) | (((lane >> 5) & 1) << 8); }
; __device__ __forceinline__ u16 f2bf(float f) { return (u16)(pk2(f, 0.f) & 0xffffu); }
; #define GLA_SBAR() __builtin_amdgcn_sched_barrier(0)
; __device__ __forceinline__ void scan_unit(const int unit, const Args& a, unsigned char* lds, const int mk_wid) {
;     ...
;               { u16* ow = ot + (4 * hi) * 256 + vt * 32 + r32;
; #pragma unroll
;                 for (int r = 0; r < 16; ++r) { const int i0 = crow(r, 0); ow[i0 * 256] = f2bf(o0[r]); ow[(i0 + 32) * 256] = f2bf(o1[r]); } }
;     ...
; #pragma unroll
;           for (int ct = 0; ct < 4; ++ct) { const int kb_ = ldsb + L_KD + v_rd_base(lane) + ct * 512;
;               const s16x4 al0 = tr_read<v_rd_off(0, 0, 0)>(kb_), ah0 = tr_read<v_rd_off(0, 0, 1)>(kb_), al1 = tr_read<v_rd_off(0, 1, 0)>(kb_), ah1 = tr_read<v_rd_off(0, 1, 1)>(kb_);
;               const s16x4 al2 = tr_read<v_rd_off(0, 2, 0)>(kb_), ah2 = tr_read<v_rd_off(0, 2, 1)>(kb_), al3 = tr_read<v_rd_off(0, 3, 0)>(kb_), ah3 = tr_read<v_rd_off(0, 3, 1)>(kb_);
;               const float* dp = dl + ct * 32 + 4 * hi;
; #pragma unroll
;               for (int rg = 0; rg < 4; ++rg) { const f32x4 d4 = *(const f32x4*)(dp + 8 * rg);
;                   S[ct][4 * rg + 0] *= d4.x; S[ct][4 * rg + 1] *= d4.y; S[ct][4 * rg + 2] *= d4.z; S[ct][4 * rg + 3] *= d4.w; }
;               asm volatile("s_waitcnt lgkmcnt(0)" ::: "memory"); GLA_SBAR();
;               S[ct] = __builtin_amdgcn_mfma_f32_32x32x16_bf16(GLA_PK(al0, ah0), GLA_PK(vl0, vh0), S[ct], 0, 0, 0);
;               S[ct] = __builtin_amdgcn_mfma_f32_32x32x16_bf16(GLA_PK(al1, ah1), GLA_PK(vl1, vh1), S[ct], 0, 0, 0);
;               S[ct] = __builtin_amdgcn_mfma_f32_32x32x16_bf16(GLA_PK(al2, ah2), GLA_PK(vl2, vh2), S[ct], 0, 0, 0);
;               S[ct] = __builtin_amdgcn_mfma_f32_32x32x16_bf16(GLA_PK(al3, ah3), GLA_PK(vl3, vh3), S[ct], 0, 0, 0); } }
	s_waitcnt lgkmcnt(2)
	v_pk_mul_f32 v[20:21], v[20:21], v[230:231]
	v_pk_mul_f32 v[22:23], v[22:23], v[232:233]
	s_waitcnt lgkmcnt(1)
	v_pk_mul_f32 v[24:25], v[24:25], v[226:227]
	v_mfma_f32_32x32x16_bf16 v[0:15], v[214:217], v[148:151], v[0:15]
	v_cvt_pk_bf16_f32 v170, v170, v186
	ds_write_b32 v246, v170
	v_cvt_pk_bf16_f32 v171, v171, v187
	ds_write_b32 v246, v171 offset:1024
	v_mul_f32_e64 v26, v26, v228
	v_mul_f32_e64 v27, v27, v229
	s_waitcnt lgkmcnt(0)
	v_mul_f32_e64 v28, v28, v210
	v_mul_f32_e64 v29, v29, v211
	v_pk_mul_f32 v[30:31], v[30:31], v[212:213]
	s_nop 1
	v_mfma_f32_32x32x16_bf16 v[16:31], v[202:205], v[136:139], v[16:31]
	v_cvt_pk_bf16_f32 v172, v172, v188
	ds_write_b32 v246, v172 offset:4096
	v_cvt_pk_bf16_f32 v173, v173, v189
	ds_write_b32 v246, v173 offset:5120
	s_add_i32 s5, s4, 0x8c00
	v_add_u32_e32 v226, s5, v154
	ds_read_b64_tr_b16 v[202:203], v226 offset:0
	ds_read_b64_tr_b16 v[204:205], v226 offset:0x800
	ds_read_b64_tr_b16 v[210:211], v226 offset:0x1000
	ds_read_b64_tr_b16 v[212:213], v226 offset:0x1800
	ds_read_b64_tr_b16 v[214:215], v226 offset:0x2000
	v_mfma_f32_32x32x16_bf16 v[16:31], v[218:221], v[140:143], v[16:31]
	v_cvt_pk_bf16_f32 v174, v174, v190
	ds_write_b32 v246, v174 offset:8192
	v_cvt_pk_bf16_f32 v175, v175, v191
	ds_write_b32 v246, v175 offset:9216
	ds_read_b64_tr_b16 v[216:217], v226 offset:0x2800
	ds_read_b64_tr_b16 v[218:219], v226 offset:0x3000
	ds_read_b64_tr_b16 v[220:221], v226 offset:0x3800
	ds_read_b128 v[226:229], v157 offset:256
	ds_read_b128 v[230:233], v157 offset:288
	s_waitcnt lgkmcnt(1)
	v_mul_f32_e64 v32, v32, v226
	v_mul_f32_e64 v33, v33, v227
	v_mfma_f32_32x32x16_bf16 v[16:31], v[222:225], v[144:147], v[16:31]
	v_cvt_pk_bf16_f32 v176, v176, v192
	ds_write_b32 v246, v176 offset:12288
	v_cvt_pk_bf16_f32 v177, v177, v193
	ds_write_b32 v246, v177 offset:13312
	v_mul_f32_e64 v34, v34, v228
	v_mul_f32_e64 v35, v35, v229
	ds_read_b128 v[226:229], v157 offset:320
	ds_read_b128 v[222:225], v157 offset:352
	s_waitcnt lgkmcnt(0)
	s_waitcnt lgkmcnt(2)
	v_pk_mul_f32 v[36:37], v[36:37], v[230:231]
	v_pk_mul_f32 v[38:39], v[38:39], v[232:233]
	s_waitcnt lgkmcnt(1)
	v_pk_mul_f32 v[40:41], v[40:41], v[226:227]
	v_mfma_f32_32x32x16_bf16 v[16:31], v[206:209], v[148:151], v[16:31]
	v_cvt_pk_bf16_f32 v178, v178, v194
	ds_write_b32 v246, v178 offset:16384
	v_cvt_pk_bf16_f32 v179, v179, v195
	ds_write_b32 v246, v179 offset:17408
	v_mul_f32_e64 v42, v42, v228
	v_mul_f32_e64 v43, v43, v229
	s_waitcnt lgkmcnt(0)
	v_mul_f32_e64 v44, v44, v222
	v_mul_f32_e64 v45, v45, v223
	v_pk_mul_f32 v[46:47], v[46:47], v[224:225]
	s_nop 1
	v_mfma_f32_32x32x16_bf16 v[32:47], v[202:205], v[136:139], v[32:47]
	v_cvt_pk_bf16_f32 v180, v180, v196
	ds_write_b32 v246, v180 offset:20480
	v_cvt_pk_bf16_f32 v181, v181, v197
	ds_write_b32 v246, v181 offset:21504
	s_add_i32 s4, s4, 0x8e00
	v_add_u32_e32 v226, s4, v154
	ds_read_b64_tr_b16 v[202:203], v226 offset:0
	ds_read_b64_tr_b16 v[204:205], v226 offset:0x800
	ds_read_b64_tr_b16 v[206:207], v226 offset:0x1000
	ds_read_b64_tr_b16 v[208:209], v226 offset:0x1800
	ds_read_b64_tr_b16 v[222:223], v226 offset:0x2000
	v_mfma_f32_32x32x16_bf16 v[32:47], v[210:213], v[140:143], v[32:47]
	v_cvt_pk_bf16_f32 v182, v182, v198
	ds_write_b32 v246, v182 offset:24576
	ds_read_b64_tr_b16 v[224:225], v226 offset:0x2800
	ds_read_b64_tr_b16 v[210:211], v226 offset:0x3000
	ds_read_b64_tr_b16 v[212:213], v226 offset:0x3800
	ds_read_b128 v[226:229], v157 offset:384
	ds_read_b128 v[230:233], v157 offset:416
	s_waitcnt lgkmcnt(1)
	v_mul_f32_e64 v48, v48, v226
	v_mul_f32_e64 v49, v49, v227
	v_mfma_f32_32x32x16_bf16 v[32:47], v[214:217], v[144:147], v[32:47]
	v_cvt_pk_bf16_f32 v183, v183, v199
	ds_write_b32 v246, v183 offset:25600
	v_mul_f32_e64 v50, v50, v228
	v_mul_f32_e64 v51, v51, v229
	ds_read_b128 v[226:229], v157 offset:448
	ds_read_b128 v[214:217], v157 offset:480
	s_waitcnt lgkmcnt(0)
	s_waitcnt lgkmcnt(2)
	v_pk_mul_f32 v[52:53], v[52:53], v[230:231]
	v_pk_mul_f32 v[54:55], v[54:55], v[232:233]
	s_waitcnt lgkmcnt(1)
	v_pk_mul_f32 v[56:57], v[56:57], v[226:227]
	v_mfma_f32_32x32x16_bf16 v[32:47], v[218:221], v[148:151], v[32:47]
	v_cvt_pk_bf16_f32 v184, v184, v200
	ds_write_b32 v246, v184 offset:28672
	v_mul_f32_e64 v58, v58, v228
	v_mul_f32_e64 v59, v59, v229
	s_waitcnt lgkmcnt(0)
	v_mul_f32_e64 v60, v60, v214
	v_mul_f32_e64 v61, v61, v215
	v_pk_mul_f32 v[62:63], v[62:63], v[216:217]
	s_nop 1
	v_mfma_f32_32x32x16_bf16 v[48:63], v[202:205], v[136:139], v[48:63]
	v_cvt_pk_bf16_f32 v185, v185, v201
	ds_write_b32 v246, v185 offset:29696
	s_add_i32 s50, s50, -1
	s_cmp_eq_u32 s50, 2
	s_waitcnt lgkmcnt(0)
	s_barrier
	v_mfma_f32_32x32x16_bf16 v[48:63], v[206:209], v[140:143], v[48:63]
	v_mfma_f32_32x32x16_bf16 v[48:63], v[222:225], v[144:147], v[48:63]
	v_mfma_f32_32x32x16_bf16 v[48:63], v[210:213], v[148:151], v[48:63]
	s_cbranch_scc1 .LBB0_447
	s_mov_b32 s5, s58
	s_branch .LBB0_418
